# v46 + prep per-tile previous-row loads issued together (de-serialized 4 load-wait groups)
# baseline (speedup 1.0000x reference)
.LBB0_880:
	s_or_b64 exec, exec, s[22:23]
	v_add_u32_e32 v62, s15, v171
	v_mad_i64_i32 v[34:35], s[10:11], v62, s17, v[100:101]
	v_and_b32_e32 v181, 0xfff, v62
	v_cmp_eq_u32_e64 s[10:11], 0, v181
	s_waitcnt lgkmcnt(0)
	s_barrier
	v_cndmask_b32_e64 v37, -1, 0, s[10:11]
	v_cndmask_b32_e64 v36, v227, 0, s[10:11]
	global_load_dwordx2 v[90:91], v[34:35], off
	global_load_dwordx2 v[60:61], v[34:35], off offset:1024
	global_load_dwordx2 v[92:93], v[34:35], off offset:2048
	global_load_dwordx2 v[134:135], v[34:35], off offset:32
	global_load_dwordx2 v[58:59], v[34:35], off offset:1056
	global_load_dwordx2 v[136:137], v[34:35], off offset:2080
	global_load_dwordx2 v[124:125], v[34:35], off offset:64
	global_load_dwordx2 v[56:57], v[34:35], off offset:1088
	global_load_dwordx2 v[126:127], v[34:35], off offset:2112
	global_load_dwordx2 v[116:117], v[34:35], off offset:96
	global_load_dwordx2 v[54:55], v[34:35], off offset:1120
	global_load_dwordx2 v[118:119], v[34:35], off offset:2144
	v_lshl_add_u64 v[34:35], v[34:35], 0, v[36:37]
	global_load_dwordx2 v[36:37], v[34:35], off
	global_load_dwordx2 v[38:39], v[34:35], off offset:1024
	global_load_dwordx2 v[40:41], v[34:35], off offset:2048
	global_load_dwordx2 v[198:199], v[34:35], off offset:32
	global_load_dwordx2 v[200:201], v[34:35], off offset:1056
	global_load_dwordx2 v[202:203], v[34:35], off offset:2080
	global_load_dwordx2 v[204:205], v[34:35], off offset:64
	global_load_dwordx2 v[206:207], v[34:35], off offset:1088
	global_load_dwordx2 v[208:209], v[34:35], off offset:2112
	global_load_dwordx2 v[210:211], v[34:35], off offset:96
	global_load_dwordx2 v[64:65], v[34:35], off offset:1120
	global_load_dwordx2 v[222:223], v[34:35], off offset:2144
	s_waitcnt vmcnt(22)
	v_lshlrev_b32_e32 v74, 16, v60
	v_and_b32_e32 v75, 0xffff0000, v60
	v_lshlrev_b32_e32 v76, 16, v61
	v_and_b32_e32 v77, 0xffff0000, v61
	s_waitcnt vmcnt(19)
	v_lshlrev_b32_e32 v138, 16, v59
	v_and_b32_e32 v139, 0xffff0000, v59
	v_lshlrev_b32_e32 v164, 16, v58
	v_and_b32_e32 v165, 0xffff0000, v58
	s_waitcnt vmcnt(16)
	v_lshlrev_b32_e32 v160, 16, v56
	v_and_b32_e32 v132, 0xffff0000, v56
	s_waitcnt vmcnt(11)
	v_cndmask_b32_e64 v170, v36, 0, s[10:11]
	v_cndmask_b32_e64 v146, v37, 0, s[10:11]
	s_waitcnt vmcnt(10)
	v_cndmask_b32_e64 v63, v38, 0, s[10:11]
	v_cndmask_b32_e64 v78, v39, 0, s[10:11]
	s_waitcnt vmcnt(9)
	v_cndmask_b32_e64 v172, v40, 0, s[10:11]
	v_cndmask_b32_e64 v169, v41, 0, s[10:11]
	v_lshlrev_b32_e32 v72, 16, v63
	v_and_b32_e32 v73, 0xffff0000, v63
	v_lshlrev_b32_e32 v60, 16, v78
	v_and_b32_e32 v61, 0xffff0000, v78
	v_pk_add_f32 v[72:73], v[72:73], v[74:75] neg_lo:[0,1] neg_hi:[0,1]
	v_pk_add_f32 v[60:61], v[60:61], v[76:77] neg_lo:[0,1] neg_hi:[0,1]
	v_lshlrev_b32_e32 v130, 16, v57
	v_and_b32_e32 v128, 0xffff0000, v57
	v_lshlrev_b32_e32 v122, 16, v54
	v_and_b32_e32 v120, 0xffff0000, v54
	v_lshlrev_b32_e32 v115, 16, v55
	v_and_b32_e32 v109, 0xffff0000, v55
	v_lshlrev_b32_e32 v166, 16, v172
	v_lshlrev_b32_e32 v196, 16, v92
	v_lshlrev_b32_e32 v194, 16, v136
	v_and_b32_e32 v136, 0xffff0000, v136
	v_lshlrev_b32_e32 v195, 16, v137
	s_waitcnt vmcnt(8)
	v_cndmask_b32_e64 v0, v198, 0, s[10:11]
	v_cndmask_b32_e64 v113, v199, 0, s[10:11]
	s_waitcnt vmcnt(7)
	v_cndmask_b32_e64 v79, v200, 0, s[10:11]
	v_cndmask_b32_e64 v80, v201, 0, s[10:11]
	s_waitcnt vmcnt(6)
	v_cndmask_b32_e64 v168, v202, 0, s[10:11]
	v_cndmask_b32_e64 v192, v203, 0, s[10:11]
	s_waitcnt vmcnt(5)
	v_cndmask_b32_e64 v131, v204, 0, s[10:11]
	v_cndmask_b32_e64 v129, v205, 0, s[10:11]
	s_waitcnt vmcnt(4)
	v_cndmask_b32_e64 v81, v206, 0, s[10:11]
	v_cndmask_b32_e64 v82, v207, 0, s[10:11]
	s_waitcnt vmcnt(3)
	v_cndmask_b32_e64 v133, v208, 0, s[10:11]
	v_cndmask_b32_e64 v188, v209, 0, s[10:11]
	v_and_b32_e32 v56, 0xffff0000, v81
	v_and_b32_e32 v57, 0xffff0000, v82
	v_sub_f32_e32 v191, v56, v132
	v_sub_f32_e32 v189, v57, v128
	s_waitcnt vmcnt(2)
	v_cndmask_b32_e64 v185, v210, 0, s[10:11]
	v_cndmask_b32_e64 v123, v211, 0, s[10:11]
	s_waitcnt vmcnt(1)
	v_cndmask_b32_e64 v83, v64, 0, s[10:11]
	s_waitcnt vmcnt(0)
	v_cndmask_b32_e64 v186, v222, 0, s[10:11]
	v_cndmask_b32_e64 v184, v223, 0, s[10:11]
	ds_read_b128 v[34:37], v180
	ds_read_b128 v[38:41], v180 offset:64
	ds_read_b128 v[50:53], v180 offset:128
	ds_read_b128 v[46:49], v180 offset:192
	ds_read_b128 v[42:45], v180 offset:256
	v_cndmask_b32_e64 v84, v65, 0, s[10:11]
	ds_read_b128 v[64:67], v179 offset:20480
	ds_read_b128 v[68:71], v179 offset:12288
	v_lshlrev_b32_e32 v63, 16, v83
	v_and_b32_e32 v54, 0xffff0000, v83
	v_sub_f32_e32 v187, v63, v122
	s_waitcnt lgkmcnt(1)
	v_pk_fma_f32 v[96:97], v[72:73], v[64:65], v[74:75]
	v_pk_fma_f32 v[94:95], v[60:61], v[66:67], v[76:77]
	s_waitcnt lgkmcnt(0)
	v_pk_mul_f32 v[144:145], v[68:69], v[96:97]
	v_pk_mul_f32 v[142:143], v[70:71], v[94:95]
	ds_read_b128 v[64:67], v179 offset:20544
	ds_read_b128 v[68:71], v179 offset:12352
	v_lshlrev_b32_e32 v74, 16, v80
	v_and_b32_e32 v75, 0xffff0000, v80
	v_lshlrev_b32_e32 v72, 16, v79
	v_and_b32_e32 v73, 0xffff0000, v79
	v_pk_add_f32 v[140:141], v[74:75], v[138:139] neg_lo:[0,1] neg_hi:[0,1]
	v_pk_add_f32 v[162:163], v[72:73], v[164:165] neg_lo:[0,1] neg_hi:[0,1]
	s_waitcnt lgkmcnt(1)
	v_pk_fma_f32 v[58:59], v[140:141], v[66:67], v[138:139]
	v_pk_fma_f32 v[64:65], v[162:163], v[64:65], v[164:165]
	s_waitcnt lgkmcnt(0)
	v_pk_mul_f32 v[58:59], v[70:71], v[58:59]
	v_pk_mul_f32 v[72:73], v[68:69], v[64:65]
	v_mul_f32_e32 v64, v59, v59
	v_pk_fma_f32 v[74:75], v[58:59], v[58:59], v[64:65] op_sel_hi:[1,1,0]
	ds_read_b128 v[64:67], v179 offset:20608
	ds_read_b128 v[68:71], v179 offset:12416
	v_lshlrev_b32_e32 v58, 16, v81
	v_lshlrev_b32_e32 v59, 16, v82
	v_sub_f32_e32 v193, v58, v160
	s_waitcnt lgkmcnt(1)
	v_fma_f32 v56, v191, v65, v132
	s_waitcnt lgkmcnt(0)
	v_mul_f32_e32 v78, v69, v56
	v_sub_f32_e32 v190, v59, v130
	v_fma_f32 v56, v189, v67, v128
	v_fma_f32 v76, v193, v64, v160
	v_fma_f32 v80, v190, v66, v130
	v_mul_f32_e32 v82, v71, v56
	ds_read_b128 v[56:59], v179 offset:20672
	ds_read_b128 v[64:67], v179 offset:12480
	v_lshlrev_b32_e32 v77, 16, v84
	v_sub_f32_e32 v121, v54, v120
	v_sub_f32_e32 v183, v77, v115
	v_and_b32_e32 v79, 0xffff0000, v84
	s_waitcnt lgkmcnt(1)
	v_fma_f32 v55, v187, v56, v122
	v_fma_f32 v54, v121, v57, v120
	v_mul_f32_e32 v77, v183, v58
	v_mov_b32_e32 v114, v68
	s_waitcnt lgkmcnt(0)
	v_mul_f32_e32 v55, v64, v55
	v_mul_f32_e32 v57, v65, v54
	v_sub_f32_e32 v182, v79, v109
	v_pk_add_f32 v[64:65], v[114:115], v[76:77]
	v_mov_b32_e32 v63, v66
	v_mul_f32_e32 v81, v182, v59
	v_pk_mul_f32 v[58:59], v[68:69], v[76:77]
	v_pk_mul_f32 v[76:77], v[62:63], v[64:65]
	v_mov_b32_e32 v79, v66
	v_mov_b32_e32 v64, v78
	v_mov_b32_e32 v108, v70
	v_mov_b32_e32 v59, v65
	v_pk_mul_f32 v[64:65], v[78:79], v[64:65]
	v_pk_add_f32 v[78:79], v[108:109], v[80:81]
	v_mul_f32_e32 v60, v143, v143
	v_pk_mul_f32 v[70:71], v[70:71], v[80:81]
	v_pk_mul_f32 v[84:85], v[66:67], v[78:79]
	v_mov_b32_e32 v83, v67
	v_mov_b32_e32 v78, v82
	v_mul_f32_e32 v54, v145, v145
	v_pk_fma_f32 v[60:61], v[142:143], v[142:143], v[60:61] op_sel_hi:[1,1,0]
	v_mov_b32_e32 v69, v66
	v_mov_b32_e32 v71, v79
	v_mov_b32_e32 v81, v67
	v_pk_mul_f32 v[66:67], v[82:83], v[78:79]
	v_pk_fma_f32 v[78:79], v[144:145], v[144:145], v[54:55] op_sel_hi:[1,1,0]
	v_mov_b32_e32 v82, v60
	v_mov_b32_e32 v54, v78
	v_mov_b32_e32 v83, v55
	v_pk_mul_f32 v[54:55], v[54:55], v[82:83]
	v_pk_add_f32 v[60:61], v[78:79], v[60:61]
	v_mul_f32_e32 v54, v73, v73
	v_mov_b32_e32 v61, v55
	v_pk_fma_f32 v[54:55], v[72:73], v[72:73], v[54:55] op_sel_hi:[1,1,0]
	v_mov_b32_e32 v72, v74
	v_mov_b32_e32 v56, v54
	v_mov_b32_e32 v73, v57
	v_mov_b32_e32 v68, v58
	v_pk_add_f32 v[54:55], v[54:55], v[74:75]
	v_pk_mul_f32 v[56:57], v[56:57], v[72:73]
	v_mov_b32_e32 v80, v70
	v_mov_b32_e32 v55, v57
	v_pk_fma_f32 v[56:57], v[68:69], v[58:59], v[64:65]
	v_pk_mul_f32 v[58:59], v[76:77], v[64:65]
	v_pk_add_f32 v[54:55], v[60:61], v[54:55]
	v_mov_b32_e32 v57, v59
	v_pk_fma_f32 v[58:59], v[80:81], v[70:71], v[66:67]
	v_pk_mul_f32 v[60:61], v[84:85], v[66:67]
	s_ashr_i32 s10, s16, 5
	v_mov_b32_e32 v59, v61
	v_pk_add_f32 v[56:57], v[56:57], v[58:59]
	s_and_b32 s10, s10, -8
	v_pk_add_f32 v[54:55], v[54:55], v[56:57]
	s_add_i32 s22, s10, s14
	v_add_f32_e32 v54, v54, v55
	ds_bpermute_b32 v55, v177, v54
	s_ashr_i32 s23, s22, 31
	s_lshl_b64 s[10:11], s[22:23], 8
	v_mfma_f32_16x16x32_bf16 v[86:89], v[2:5], v[34:37], 0
	v_lshlrev_b32_e32 v114, 16, v170
	s_waitcnt lgkmcnt(0)
	v_add_f32_e32 v54, v54, v55
	ds_bpermute_b32 v55, v178, v54
	v_lshlrev_b32_e32 v108, 16, v90
	v_sub_f32_e32 v114, v114, v108
	s_waitcnt lgkmcnt(0)
	v_add_f32_e32 v54, v54, v55
	v_max_f32_e32 v54, 0x179abe15, v54
	v_rsq_f32_e32 v112, v54
	v_bfe_u32 v54, v62, 4, 8
	v_or_b32_e32 v54, s10, v54
	s_movk_i32 s10, 0x3000
	v_mad_u64_u32 v[110:111], s[12:13], v54, s10, v[102:103]
	ds_read_b128 v[66:69], v179 offset:8192
	ds_read_b128 v[62:65], v179 offset:10240
	ds_read_b128 v[58:61], v179 offset:14336
	ds_read_b128 v[54:57], v179 offset:16384
	ds_read_b128 v[70:73], v179 offset:18432
	ds_read_b128 v[74:77], v179 offset:22528
	ds_read_b128 v[78:81], v174 offset:32768
	ds_read_b128 v[82:85], v174 offset:36864
	s_waitcnt lgkmcnt(7)
	v_add_f32_e32 v66, v66, v86
	s_waitcnt lgkmcnt(3)
	v_fmac_f32_e32 v108, v114, v70
	v_sub_f32_e32 v70, v166, v196
	s_waitcnt lgkmcnt(2)
	v_fmac_f32_e32 v196, v70, v74
	v_max_f32_e64 v70, -v66, 0
	v_mul_f32_e64 v66, |v66|, s65
	v_exp_f32_e32 v66, v66
	s_waitcnt lgkmcnt(1)
	v_mfma_f32_16x16x32_bf16 v[78:81], v[78:81], v[50:53], 0
	v_mad_i32_i24 v111, s11, v228, v111
	v_mul_f32_e64 v144, v144, -v112
	v_add_f32_e32 v66, 1.0, v66
	s_waitcnt lgkmcnt(0)
	v_mfma_f32_16x16x32_bf16 v[78:81], v[82:85], v[46:49], v[78:81]
	ds_read_b128 v[82:85], v174 offset:40960
	v_cmp_gt_f32_e64 s[10:11], s89, v66
	v_xor_b32_e32 v166, 0x80000000, v144
	s_waitcnt lgkmcnt(0)
	v_mfma_f32_16x16x32_bf16 v[78:81], v[82:85], v[42:45], v[78:81]
	v_cndmask_b32_e64 v74, 0, 32, s[10:11]
	v_ldexp_f32 v66, v66, v74
	v_log_f32_e32 v66, v66
	v_mfma_f32_16x16x32_bf16 v[82:85], v[6:9], v[38:41], 0
	v_mul_f32_e32 v74, 0x3f317217, v66
	v_fma_f32 v74, v66, s2, -v74
	v_fmac_f32_e32 v74, 0x3377d1cf, v66
	v_fmac_f32_e32 v74, 0x3f317217, v66
	v_cmp_lt_f32_e64 s[12:13], |v66|, s62
	s_nop 2
	v_add_f32_e32 v62, v62, v82
	v_mul_f32_e32 v62, 0xbfb8aa3b, v62
	v_cndmask_b32_e64 v66, v66, v74, s[12:13]
	v_cndmask_b32_e64 v74, 0, v229, s[10:11]
	v_sub_f32_e32 v66, v66, v74
	v_add_f32_e32 v66, v70, v66
	v_sub_f32_e32 v66, -0.5, v66
	v_mul_f32_e32 v66, 0x3fb8aa3b, v66
	v_exp_f32_e32 v62, v62
	v_exp_f32_e32 v66, v66
	v_and_b32_e32 v82, 0xffff0000, v92
	v_add_f32_e32 v63, v63, v83
	v_add_f32_e32 v62, 1.0, v62
	v_mul_f32_e32 v66, 0xbfb8aa3b, v66
	v_rcp_f32_e32 v62, v62
	v_exp_f32_e32 v66, v66
	v_mul_f32_e32 v63, 0xbfb8aa3b, v63
	v_exp_f32_e32 v63, v63
	v_add_f32_e32 v70, -1.0, v62
	v_sub_f32_e32 v114, 1.0, v66
	v_fma_f32 v167, v58, v70, 1.0
	v_mul_f32_e32 v173, v108, v66
	v_and_b32_e32 v58, 0xffff0000, v90
	v_and_b32_e32 v66, 0xffff0000, v170
	v_and_b32_e32 v70, 0xffff0000, v172
	v_sub_f32_e32 v66, v66, v58
	v_fmac_f32_e32 v58, v66, v71
	v_sub_f32_e32 v66, v70, v82
	v_fmac_f32_e32 v82, v66, v75
	v_add_f32_e32 v66, v67, v87
	v_max_f32_e64 v67, -v66, 0
	v_mul_f32_e64 v66, |v66|, s65
	v_exp_f32_e32 v66, v66
	v_add_f32_e32 v63, 1.0, v63
	v_lshlrev_b32_e32 v83, 16, v169
	v_lshlrev_b32_e32 v90, 16, v93
	v_add_f32_e32 v66, 1.0, v66
	v_cmp_gt_f32_e64 s[10:11], s89, v66
	v_add_f32_e32 v64, v64, v84
	v_mul_f32_e32 v64, 0xbfb8aa3b, v64
	v_cndmask_b32_e64 v70, 0, 32, s[10:11]
	v_ldexp_f32 v66, v66, v70
	v_log_f32_e32 v66, v66
	v_exp_f32_e32 v64, v64
	v_add_f32_e32 v65, v65, v85
	v_mul_f32_e32 v65, 0xbfb8aa3b, v65
	v_mul_f32_e32 v70, 0x3f317217, v66
	v_fma_f32 v70, v66, s2, -v70
	v_fmac_f32_e32 v70, 0x3377d1cf, v66
	v_fmac_f32_e32 v70, 0x3f317217, v66
	v_cmp_lt_f32_e64 s[12:13], |v66|, s62
	v_add_f32_e32 v64, 1.0, v64
	v_rcp_f32_e32 v64, v64
	v_cndmask_b32_e64 v66, v66, v70, s[12:13]
	v_cndmask_b32_e64 v70, 0, v229, s[10:11]
	v_sub_f32_e32 v66, v66, v70
	v_add_f32_e32 v66, v67, v66
	v_sub_f32_e32 v66, -0.5, v66
	v_mul_f32_e32 v66, 0x3fb8aa3b, v66
	v_exp_f32_e32 v66, v66
	v_lshlrev_b32_e32 v70, 16, v91
	v_exp_f32_e32 v65, v65
	v_mul_f32_e64 v84, v142, -v112
	v_mul_f32_e32 v66, 0xbfb8aa3b, v66
	v_exp_f32_e32 v67, v66
	v_rcp_f32_e32 v66, v63
	v_add_f32_e32 v65, 1.0, v65
	v_lshlrev_b32_e32 v170, 16, v134
	v_sub_f32_e32 v71, 1.0, v67
	v_add_f32_e32 v63, -1.0, v66
	v_fma_f32 v75, v59, v63, 1.0
	v_mul_f32_e32 v59, v58, v67
	v_lshlrev_b32_e32 v67, 16, v146
	v_sub_f32_e32 v67, v67, v70
	v_fmac_f32_e32 v70, v67, v72
	v_sub_f32_e32 v67, v83, v90
	v_fmac_f32_e32 v90, v67, v76
	v_add_f32_e32 v67, v68, v88
	v_max_f32_e64 v68, -v67, 0
	v_mul_f32_e64 v67, |v67|, s65
	v_exp_f32_e32 v67, v67
	v_and_b32_e32 v88, 0xffff0000, v93
	v_cvt_pk_bf16_f32 v76, v114, v71
	v_mul_f32_e64 v63, v145, -v112
	v_add_f32_e32 v67, 1.0, v67
	v_cmp_gt_f32_e64 s[10:11], s89, v67
	v_xor_b32_e32 v74, 0x80000000, v63
	v_xor_b32_e32 v86, 0x80000000, v84
	v_cndmask_b32_e64 v72, 0, 32, s[10:11]
	v_ldexp_f32 v67, v67, v72
	v_log_f32_e32 v67, v67
	v_and_b32_e32 v114, 0xffff0000, v134
	v_mul_f32_e32 v72, 0x3f317217, v67
	v_fma_f32 v72, v67, s2, -v72
	v_fmac_f32_e32 v72, 0x3377d1cf, v67
	v_fmac_f32_e32 v72, 0x3f317217, v67
	v_cmp_lt_f32_e64 s[12:13], |v67|, s62
	s_nop 1
	v_cndmask_b32_e64 v67, v67, v72, s[12:13]
	v_cndmask_b32_e64 v72, 0, v229, s[10:11]
	v_sub_f32_e32 v67, v67, v72
	v_add_f32_e32 v67, v68, v67
	v_add_f32_e32 v68, -1.0, v64
	v_fma_f32 v87, v60, v68, 1.0
	v_and_b32_e32 v60, 0xffff0000, v91
	v_and_b32_e32 v68, 0xffff0000, v146
	v_and_b32_e32 v72, 0xffff0000, v169
	v_sub_f32_e32 v68, v68, v60
	v_fmac_f32_e32 v60, v68, v73
	v_sub_f32_e32 v68, v72, v88
	v_fmac_f32_e32 v88, v68, v77
	v_add_f32_e32 v68, v69, v89
	v_max_f32_e64 v69, -v68, 0
	v_mul_f32_e64 v68, |v68|, s65
	v_exp_f32_e32 v68, v68
	v_sub_f32_e32 v67, -0.5, v67
	v_mul_f32_e32 v67, 0x3fb8aa3b, v67
	v_exp_f32_e32 v67, v67
	v_add_f32_e32 v68, 1.0, v68
	v_cmp_gt_f32_e64 s[10:11], s89, v68
	v_mov_b32_e32 v146, v164
	v_mul_f32_e32 v67, 0xbfb8aa3b, v67
	v_cndmask_b32_e64 v72, 0, 32, s[10:11]
	v_ldexp_f32 v68, v68, v72
	v_log_f32_e32 v68, v68
	v_exp_f32_e32 v67, v67
	v_mov_b32_e32 v164, v138
	v_mov_b32_e32 v169, v147
	v_mul_f32_e32 v72, 0x3f317217, v68
	v_fma_f32 v72, v68, s2, -v72
	v_fmac_f32_e32 v72, 0x3377d1cf, v68
	v_fmac_f32_e32 v72, 0x3f317217, v68
	v_cmp_lt_f32_e64 s[12:13], |v68|, s62
	v_sub_f32_e32 v83, 1.0, v67
	v_mul_f32_e32 v67, v70, v67
	v_cndmask_b32_e64 v68, v68, v72, s[12:13]
	v_cndmask_b32_e64 v72, 0, v229, s[10:11]
	v_sub_f32_e32 v68, v68, v72
	v_add_f32_e32 v68, v69, v68
	v_sub_f32_e32 v68, -0.5, v68
	v_mul_f32_e32 v68, 0x3fb8aa3b, v68
	v_exp_f32_e32 v68, v68
	s_nop 0
	v_mul_f32_e32 v68, 0xbfb8aa3b, v68
	v_exp_f32_e32 v69, v68
	v_rcp_f32_e32 v68, v65
	v_sub_f32_e32 v77, 1.0, v69
	v_add_f32_e32 v65, -1.0, v68
	v_cvt_pk_bf16_f32 v77, v83, v77
	global_store_dwordx2 v[110:111], v[76:77], off
	v_cvt_pk_bf16_f32 v76, v173, v59
	v_fma_f32 v73, v61, v65, 1.0
	v_mul_f32_e32 v61, v60, v69
	v_cvt_pk_bf16_f32 v77, v67, v61
	global_store_dwordx2 v[110:111], v[76:77], off offset:2048
	v_cvt_pk_bf16_f32 v76, v144, v63
	v_add_co_u32_e64 v144, s[10:11], s25, v110
	v_lshlrev_b32_e32 v59, 16, v0
	s_nop 0
	v_addc_co_u32_e64 v145, s[10:11], 0, v111, s[10:11]
	s_movk_i32 s10, 0x2000
	s_nop 0
	v_add_co_u32_e64 v142, s[10:11], s10, v110
	v_mov_b32_e32 v63, v96
	v_mul_f32_e64 v65, v143, -v112
	v_cvt_pk_bf16_f32 v77, v84, v65
	v_addc_co_u32_e64 v143, s[10:11], 0, v111, s[10:11]
	v_sub_f32_e32 v197, v59, v170
	v_and_b32_e32 v59, 0xffff0000, v168
	v_pk_mul_f32 v[62:63], v[166:167], v[62:63]
	v_mov_b32_e32 v67, v97
	global_store_dwordx2 v[142:143], v[76:77], off offset:-4096
	v_sub_f32_e32 v200, v59, v136
	v_lshlrev_b32_e32 v59, 16, v113
	v_pk_mul_f32 v[76:77], v[108:109], v[62:63] op_sel_hi:[0,1]
	v_pk_mul_f32 v[66:67], v[74:75], v[66:67]
	v_xor_b32_e32 v72, 0x80000000, v65
	v_fma_f32 v138, v54, v77, 0
	v_pk_mul_f32 v[74:75], v[58:59], v[66:67] op_sel_hi:[0,1]
	v_mov_b32_e32 v65, v94
	v_fmac_f32_e32 v138, v55, v75
	v_pk_mul_f32 v[54:55], v[86:87], v[64:65]
	v_lshlrev_b32_e32 v61, 16, v168
	v_and_b32_e32 v0, 0xffff0000, v0
	v_pk_mul_f32 v[64:65], v[70:71], v[54:55] op_sel_hi:[0,1]
	v_mov_b32_e32 v69, v95
	v_sub_f32_e32 v198, v61, v194
	v_sub_f32_e32 v134, v0, v114
	v_lshlrev_b32_e32 v0, 16, v135
	v_lshlrev_b32_e32 v61, 16, v192
	v_pk_fma_f32 v[84:85], v[108:109], v[62:63], 0 op_sel_hi:[0,1,0]
	v_fmac_f32_e32 v138, v56, v65
	v_pk_mul_f32 v[64:65], v[72:73], v[68:69]
	v_sub_f32_e32 v201, v59, v0
	v_pk_fma_f32 v[58:59], v[58:59], v[66:67], v[84:85] op_sel_hi:[0,1,1]
	v_pk_mul_f32 v[68:69], v[60:61], v[64:65] op_sel_hi:[0,1]
	v_pk_fma_f32 v[58:59], v[70:71], v[54:55], v[58:59] op_sel_hi:[0,1,1]
	v_fmac_f32_e32 v138, v57, v69
	v_cvt_pk_bf16_f32 v56, v62, v66
	v_cvt_pk_bf16_f32 v57, v54, v64
	global_store_dwordx2 v[144:145], v[56:57], off offset:2048
	v_cvt_pk_bf16_f32 v54, v63, v67
	v_cvt_pk_bf16_f32 v55, v55, v65
	global_store_dwordx2 v[142:143], v[54:55], off
	v_cvt_pk_bf16_f32 v54, v196, v82
	v_cvt_pk_bf16_f32 v55, v90, v88
	global_store_dwordx2 v[142:143], v[54:55], off offset:2048
	v_cvt_pk_bf16_f32 v54, v78, v79
	v_cvt_pk_bf16_f32 v55, v80, v81
	global_store_dwordx2 v[106:107], v[54:55], off offset:-1024
	v_sub_f32_e32 v202, v61, v195
	v_pk_fma_f32 v[172:173], v[60:61], v[64:65], v[58:59] op_sel_hi:[0,1,1]
	ds_read_b128 v[78:81], v179 offset:8256
	ds_read_b128 v[74:77], v179 offset:10304
	ds_read_b128 v[58:61], v179 offset:12352
	ds_read_b128 v[62:65], v179 offset:14400
	ds_read_b128 v[54:57], v179 offset:16448
	ds_read_b128 v[86:89], v179 offset:18496
	ds_read_b128 v[82:85], v179 offset:22592
	ds_read_b128 v[66:69], v179 offset:20544
	ds_read_b128 v[70:73], v174 offset:33792
	ds_read_b128 v[90:93], v174 offset:37888
	s_waitcnt lgkmcnt(1)
	v_mfma_f32_16x16x32_bf16 v[70:73], v[70:73], v[50:53], 0
	v_fmac_f32_e32 v194, v198, v82
	v_fmac_f32_e32 v170, v197, v86
	v_mov_b32_e32 v198, v162
	s_waitcnt lgkmcnt(0)
	v_mfma_f32_16x16x32_bf16 v[70:73], v[90:93], v[46:49], v[70:73]
	ds_read_b128 v[90:93], v174 offset:41984
	v_mov_b32_e32 v199, v62
	v_mov_b32_e32 v196, v66
	s_waitcnt lgkmcnt(0)
	v_mfma_f32_16x16x32_bf16 v[70:73], v[90:93], v[42:45], v[70:73]
	v_mov_b32_e32 v168, v165
	v_fmac_f32_e32 v114, v134, v87
	v_mov_b32_e32 v165, v147
	v_mfma_f32_16x16x32_bf16 v[90:93], v[14:17], v[38:41], 0
	v_fmac_f32_e32 v136, v200, v83
	v_mov_b32_e32 v87, v64
	v_fmac_f32_e32 v0, v201, v88
	v_mfma_f32_16x16x32_bf16 v[94:97], v[10:13], v[34:37], 0
	v_fmac_f32_e32 v195, v202, v84
	s_nop 2
	v_add_f32_e32 v74, v74, v90
	v_mul_f32_e32 v74, 0xbfb8aa3b, v74
	v_exp_f32_e32 v74, v74
	v_lshlrev_b32_e32 v108, 16, v124
	v_add_f32_e32 v78, v78, v94
	v_max_f32_e64 v82, -v78, 0
	v_mul_f32_e64 v78, |v78|, s65
	v_exp_f32_e32 v78, v78
	v_add_f32_e32 v74, 1.0, v74
	v_rcp_f32_e32 v166, v74
	v_add_f32_e32 v78, 1.0, v78
	v_cmp_gt_f32_e64 s[10:11], s89, v78
	v_add_f32_e32 v197, -1.0, v166
	v_pk_fma_f32 v[196:197], v[198:199], v[196:197], v[146:147]
	v_cndmask_b32_e64 v86, 0, 32, s[10:11]
	v_ldexp_f32 v78, v78, v86
	v_log_f32_e32 v78, v78
	v_mul_f32_e64 v58, v58, -v196
	v_mul_f32_e32 v66, v112, v58
	v_add_f32_e32 v58, v79, v95
	v_max_f32_e64 v62, -v58, 0
	v_mul_f32_e64 v58, |v58|, s65
	v_exp_f32_e32 v58, v58
	v_mul_f32_e32 v86, 0x3f317217, v78
	v_fma_f32 v86, v78, s2, -v86
	v_fmac_f32_e32 v86, 0x3377d1cf, v78
	v_fmac_f32_e32 v86, 0x3f317217, v78
	v_cmp_lt_f32_e64 s[12:13], |v78|, s62
	v_add_f32_e32 v58, 1.0, v58
	v_xor_b32_e32 v198, 0x80000000, v66
	v_cndmask_b32_e64 v78, v78, v86, s[12:13]
	v_cndmask_b32_e64 v86, 0, v229, s[10:11]
	v_cmp_gt_f32_e64 s[10:11], s89, v58
	v_mov_b32_e32 v199, v196
	v_mov_b32_e32 v167, v197
	v_cndmask_b32_e64 v74, 0, 32, s[10:11]
	v_ldexp_f32 v58, v58, v74
	v_log_f32_e32 v58, v58
	v_pk_mul_f32 v[166:167], v[198:199], v[166:167]
	v_sub_f32_e32 v78, v78, v86
	v_pk_mul_f32 v[196:197], v[170:171], v[166:167] op_sel_hi:[0,1]
	v_mul_f32_e32 v74, 0x3f317217, v58
	v_fma_f32 v74, v58, s2, -v74
	v_fmac_f32_e32 v74, 0x3377d1cf, v58
	v_fmac_f32_e32 v74, 0x3f317217, v58
	v_cmp_lt_f32_e64 s[12:13], |v58|, s62
	v_fmac_f32_e32 v138, v54, v197
	v_add_f32_e32 v78, v82, v78
	v_cndmask_b32_e64 v58, v58, v74, s[12:13]
	v_cndmask_b32_e64 v74, 0, v229, s[10:11]
	v_sub_f32_e32 v58, v58, v74
	v_add_f32_e32 v58, v62, v58
	v_sub_f32_e32 v58, -0.5, v58
	v_mul_f32_e32 v58, 0x3fb8aa3b, v58
	v_exp_f32_e32 v58, v58
	v_mov_b32_e32 v62, v163
	v_mov_b32_e32 v74, v67
	v_sub_f32_e32 v78, -0.5, v78
	v_mul_f32_e32 v58, 0xbfb8aa3b, v58
	v_exp_f32_e32 v79, v58
	v_add_f32_e32 v58, v75, v91
	v_mul_f32_e32 v58, 0xbfb8aa3b, v58
	v_exp_f32_e32 v58, v58
	v_sub_f32_e32 v90, 1.0, v79
	v_mul_f32_e32 v78, 0x3fb8aa3b, v78
	v_exp_f32_e32 v78, v78
	v_add_f32_e32 v58, 1.0, v58
	v_rcp_f32_e32 v58, v58
	v_mov_b32_e32 v86, v140
	v_mul_f32_e32 v78, 0xbfb8aa3b, v78
	v_exp_f32_e32 v82, v78
	v_add_f32_e32 v75, -1.0, v58
	v_pk_fma_f32 v[62:63], v[62:63], v[74:75], v[168:169]
	v_pk_fma_f32 v[172:173], v[170:171], v[166:167], v[172:173] op_sel_hi:[0,1,1]
	v_mul_f32_e64 v59, v59, -v62
	v_mul_f32_e32 v67, v112, v59
	v_xor_b32_e32 v74, 0x80000000, v67
	v_mov_b32_e32 v75, v62
	v_mov_b32_e32 v59, v63
	v_pk_mul_f32 v[58:59], v[74:75], v[58:59]
	v_sub_f32_e32 v78, 1.0, v82
	v_pk_mul_f32 v[62:63], v[114:115], v[58:59] op_sel_hi:[0,1]
	v_add_f32_e32 v62, v80, v96
	v_fmac_f32_e32 v138, v55, v63
	v_max_f32_e64 v63, -v62, 0
	v_mul_f32_e64 v62, |v62|, s65
	v_exp_f32_e32 v62, v62
	v_mul_f32_e32 v55, v114, v79
	v_mul_f32_e32 v54, v170, v82
	v_mov_b32_e32 v82, v68
	v_add_f32_e32 v62, 1.0, v62
	v_cmp_gt_f32_e64 s[10:11], s89, v62
	v_pk_fma_f32 v[74:75], v[114:115], v[58:59], v[172:173] op_sel_hi:[0,1,1]
	v_mov_b32_e32 v146, v139
	v_cndmask_b32_e64 v79, 0, 32, s[10:11]
	v_ldexp_f32 v62, v62, v79
	v_log_f32_e32 v62, v62
	v_lshlrev_b32_e32 v114, 16, v126
	v_mul_f32_e32 v79, 0x3f317217, v62
	v_fma_f32 v79, v62, s2, -v79
	v_fmac_f32_e32 v79, 0x3377d1cf, v62
	v_fmac_f32_e32 v79, 0x3f317217, v62
	v_cmp_lt_f32_e64 s[12:13], |v62|, s62
	s_nop 1
	v_cndmask_b32_e64 v62, v62, v79, s[12:13]
	v_cndmask_b32_e64 v79, 0, v229, s[10:11]
	v_sub_f32_e32 v62, v62, v79
	v_add_f32_e32 v62, v63, v62
	v_sub_f32_e32 v62, -0.5, v62
	v_mul_f32_e32 v62, 0x3fb8aa3b, v62
	v_exp_f32_e32 v62, v62
	s_nop 0
	v_mul_f32_e32 v62, 0xbfb8aa3b, v62
	v_exp_f32_e32 v79, v62
	v_add_f32_e32 v62, v76, v92
	v_mul_f32_e32 v62, 0xbfb8aa3b, v62
	v_exp_f32_e32 v62, v62
	v_sub_f32_e32 v80, 1.0, v79
	v_mul_f32_e32 v79, v0, v79
	v_add_f32_e32 v62, 1.0, v62
	v_rcp_f32_e32 v62, v62
	s_nop 0
	v_add_f32_e32 v83, -1.0, v62
	v_pk_fma_f32 v[82:83], v[86:87], v[82:83], v[164:165]
	s_nop 0
	v_mul_f32_e64 v60, v60, -v82
	v_mul_f32_e32 v76, v112, v60
	v_xor_b32_e32 v86, 0x80000000, v76
	v_mov_b32_e32 v87, v82
	v_mov_b32_e32 v63, v83
	v_pk_mul_f32 v[62:63], v[86:87], v[62:63]
	v_and_b32_e32 v60, 0xffff0000, v192
	v_pk_mul_f32 v[82:83], v[0:1], v[62:63] op_sel_hi:[0,1]
	v_pk_fma_f32 v[162:163], v[0:1], v[62:63], v[74:75] op_sel_hi:[0,1,1]
	v_fmac_f32_e32 v138, v56, v83
	v_and_b32_e32 v0, 0xffff0000, v135
	v_and_b32_e32 v56, 0xffff0000, v113
	v_and_b32_e32 v82, 0xffff0000, v137
	v_sub_f32_e32 v56, v56, v0
	v_fmac_f32_e32 v0, v56, v89
	v_sub_f32_e32 v56, v60, v82
	v_fmac_f32_e32 v82, v56, v85
	v_add_f32_e32 v56, v81, v97
	v_max_f32_e64 v60, -v56, 0
	v_mul_f32_e64 v56, |v56|, s65
	v_exp_f32_e32 v56, v56
	v_mov_b32_e32 v74, v69
	v_mfma_f32_16x16x32_bf16 v[94:97], v[18:21], v[34:37], 0
	v_lshlrev_b32_e32 v113, 16, v131
	v_add_f32_e32 v56, 1.0, v56
	v_cmp_gt_f32_e64 s[10:11], s89, v56
	v_sub_f32_e32 v113, v113, v108
	s_nop 0
	v_cndmask_b32_e64 v64, 0, 32, s[10:11]
	v_ldexp_f32 v56, v56, v64
	v_log_f32_e32 v56, v56
	s_nop 0
	v_mul_f32_e32 v64, 0x3f317217, v56
	v_fma_f32 v64, v56, s2, -v64
	v_fmac_f32_e32 v64, 0x3377d1cf, v56
	v_fmac_f32_e32 v64, 0x3f317217, v56
	v_cmp_lt_f32_e64 s[12:13], |v56|, s62
	s_nop 1
	v_cndmask_b32_e64 v56, v56, v64, s[12:13]
	v_cndmask_b32_e64 v64, 0, v229, s[10:11]
	v_sub_f32_e32 v56, v56, v64
	v_add_f32_e32 v56, v60, v56
	v_add_f32_e32 v60, v77, v93
	v_mul_f32_e32 v60, 0xbfb8aa3b, v60
	v_exp_f32_e32 v60, v60
	v_sub_f32_e32 v56, -0.5, v56
	v_mul_f32_e32 v56, 0x3fb8aa3b, v56
	v_exp_f32_e32 v56, v56
	v_add_f32_e32 v60, 1.0, v60
	v_rcp_f32_e32 v60, v60
	v_mov_b32_e32 v64, v141
	v_mul_f32_e32 v56, 0xbfb8aa3b, v56
	v_exp_f32_e32 v56, v56
	v_add_f32_e32 v75, -1.0, v60
	v_pk_fma_f32 v[64:65], v[64:65], v[74:75], v[146:147]
	v_sub_f32_e32 v81, 1.0, v56
	v_mul_f32_e64 v61, v61, -v64
	v_mul_f32_e32 v74, v112, v61
	v_xor_b32_e32 v68, 0x80000000, v74
	v_mov_b32_e32 v69, v64
	v_mov_b32_e32 v61, v65
	v_pk_mul_f32 v[134:135], v[68:69], v[60:61]
	s_nop 0
	v_mul_f32_e32 v60, v0, v135
	v_fmac_f32_e32 v138, v57, v60
	v_mul_f32_e32 v60, v0, v56
	v_cvt_pk_bf16_f32 v56, v78, v90
	v_cvt_pk_bf16_f32 v57, v80, v81
	global_store_dwordx2 v[110:111], v[56:57], off offset:512
	v_cvt_pk_bf16_f32 v54, v54, v55
	v_cvt_pk_bf16_f32 v55, v79, v60
	global_store_dwordx2 v[110:111], v[54:55], off offset:2560
	v_cvt_pk_bf16_f32 v54, v66, v67
	v_cvt_pk_bf16_f32 v55, v76, v74
	global_store_dwordx2 v[144:145], v[54:55], off offset:512
	v_cvt_pk_bf16_f32 v54, v166, v58
	v_cvt_pk_bf16_f32 v55, v62, v134
	global_store_dwordx2 v[144:145], v[54:55], off offset:2560
	v_cvt_pk_bf16_f32 v54, v167, v59
	v_cvt_pk_bf16_f32 v55, v63, v135
	global_store_dwordx2 v[142:143], v[54:55], off offset:512
	v_cvt_pk_bf16_f32 v54, v194, v136
	v_cvt_pk_bf16_f32 v55, v195, v82
	global_store_dwordx2 v[142:143], v[54:55], off offset:2560
	v_cvt_pk_bf16_f32 v54, v70, v71
	v_cvt_pk_bf16_f32 v55, v72, v73
	global_store_dwordx2 v[106:107], v[54:55], off offset:-512
	ds_read_b128 v[74:77], v179 offset:8320
	ds_read_b128 v[70:73], v179 offset:10368
	ds_read_b128 v[66:69], v179 offset:12416
	ds_read_b128 v[62:65], v179 offset:14464
	ds_read_b128 v[54:57], v179 offset:16512
	ds_read_b128 v[86:89], v179 offset:18560
	ds_read_b128 v[78:81], v179 offset:22656
	ds_read_b128 v[82:85], v179 offset:20608
	ds_read_b128 v[58:61], v174 offset:34816
	ds_read_b128 v[90:93], v174 offset:38912
	v_lshlrev_b32_e32 v136, 16, v133
	s_waitcnt lgkmcnt(4)
	v_fmac_f32_e32 v108, v113, v86
	v_sub_f32_e32 v86, v136, v114
	v_add_f32_e32 v74, v74, v94
	s_waitcnt lgkmcnt(3)
	v_fmac_f32_e32 v114, v86, v78
	v_max_f32_e64 v78, -v74, 0
	v_mul_f32_e64 v74, |v74|, s65
	v_exp_f32_e32 v74, v74
	s_waitcnt lgkmcnt(1)
	v_mfma_f32_16x16x32_bf16 v[58:61], v[58:61], v[50:53], 0
	v_mul_f32_e32 v136, v193, v82
	v_mov_b32_e32 v164, v66
	v_add_f32_e32 v74, 1.0, v74
	s_waitcnt lgkmcnt(0)
	v_mfma_f32_16x16x32_bf16 v[58:61], v[90:93], v[46:49], v[58:61]
	ds_read_b128 v[90:93], v174 offset:43008
	v_cmp_gt_f32_e64 s[10:11], s89, v74
	v_mov_b32_e32 v165, v62
	s_waitcnt lgkmcnt(0)
	v_mfma_f32_16x16x32_bf16 v[58:61], v[90:93], v[42:45], v[58:61]
	v_cndmask_b32_e64 v82, 0, 32, s[10:11]
	v_ldexp_f32 v74, v74, v82
	v_log_f32_e32 v74, v74
	v_mfma_f32_16x16x32_bf16 v[90:93], v[22:25], v[38:41], 0
	v_and_b32_e32 v66, 0xffff0000, v124
	v_and_b32_e32 v62, 0xffff0000, v131
	v_mul_f32_e32 v82, 0x3f317217, v74
	v_fma_f32 v82, v74, s2, -v82
	v_fmac_f32_e32 v82, 0x3377d1cf, v74
	v_fmac_f32_e32 v82, 0x3f317217, v74
	v_cmp_lt_f32_e64 s[12:13], |v74|, s62
	s_nop 0
	v_add_f32_e32 v70, v70, v90
	v_mul_f32_e32 v70, 0xbfb8aa3b, v70
	v_cndmask_b32_e64 v74, v74, v82, s[12:13]
	v_cndmask_b32_e64 v82, 0, v229, s[10:11]
	v_sub_f32_e32 v74, v74, v82
	v_add_f32_e32 v74, v78, v74
	v_sub_f32_e32 v74, -0.5, v74
	v_mul_f32_e32 v74, 0x3fb8aa3b, v74
	v_exp_f32_e32 v70, v70
	v_exp_f32_e32 v74, v74
	v_and_b32_e32 v124, 0xffff0000, v126
	v_sub_f32_e32 v62, v62, v66
	v_add_f32_e32 v70, 1.0, v70
	v_mul_f32_e32 v74, 0xbfb8aa3b, v74
	v_rcp_f32_e32 v137, v70
	v_exp_f32_e32 v74, v74
	v_and_b32_e32 v70, 0xffff0000, v133
	v_fmac_f32_e32 v66, v62, v87
	v_sub_f32_e32 v62, v70, v124
	v_pk_add_f32 v[140:141], v[136:137], v[160:161]
	v_fmac_f32_e32 v124, v62, v79
	v_add_f32_e32 v62, v75, v95
	v_sub_f32_e32 v139, 1.0, v74
	v_pk_mul_f32 v[166:167], v[164:165], v[140:141]
	v_pk_fma_f32 v[164:165], v[164:165], v[140:141], s[2:3]
	v_pk_mov_b32 v[136:137], v[136:137], v[140:141] op_sel:[1,0]
	v_mul_f32_e32 v140, v108, v74
	v_max_f32_e64 v74, -v62, 0
	v_mul_f32_e64 v62, |v62|, s65
	v_exp_f32_e32 v62, v62
	v_mul_f32_e32 v70, v191, v83
	v_mov_b32_e32 v133, v161
	v_add_f32_e32 v72, v72, v92
	v_add_f32_e32 v62, 1.0, v62
	v_cmp_gt_f32_e64 s[10:11], s89, v62
	v_mul_f32_e32 v72, 0xbfb8aa3b, v72
	v_exp_f32_e32 v72, v72
	v_cndmask_b32_e64 v75, 0, 32, s[10:11]
	v_ldexp_f32 v62, v62, v75
	v_log_f32_e32 v62, v62
	v_add_f32_e32 v72, 1.0, v72
	v_mov_b32_e32 v86, v68
	v_mov_b32_e32 v87, v64
	v_mul_f32_e32 v75, 0x3f317217, v62
	v_fma_f32 v75, v62, s2, -v75
	v_fmac_f32_e32 v75, 0x3377d1cf, v62
	v_fmac_f32_e32 v75, 0x3f317217, v62
	v_cmp_lt_f32_e64 s[12:13], |v62|, s62
	v_and_b32_e32 v68, 0xffff0000, v125
	v_and_b32_e32 v64, 0xffff0000, v129
	v_cndmask_b32_e64 v62, v62, v75, s[12:13]
	v_cndmask_b32_e64 v75, 0, v229, s[10:11]
	v_sub_f32_e32 v62, v62, v75
	v_add_f32_e32 v62, v74, v62
	v_sub_f32_e32 v62, -0.5, v62
	v_mul_f32_e32 v62, 0x3fb8aa3b, v62
	v_exp_f32_e32 v62, v62
	v_rcp_f32_e32 v83, v72
	v_and_b32_e32 v72, 0xffff0000, v188
	v_sub_f32_e32 v64, v64, v68
	v_mul_f32_e32 v62, 0xbfb8aa3b, v62
	v_exp_f32_e32 v82, v62
	v_add_f32_e32 v62, v71, v91
	v_mul_f32_e32 v62, 0xbfb8aa3b, v62
	v_exp_f32_e32 v62, v62
	v_fmac_f32_e32 v68, v64, v89
	v_mov_b32_e32 v113, v147
	v_sub_f32_e32 v126, 1.0, v82
	v_add_f32_e32 v62, 1.0, v62
	v_rcp_f32_e32 v71, v62
	v_mov_b32_e32 v62, v67
	v_mov_b32_e32 v131, v161
	v_pk_mul_f32 v[166:167], v[112:113], v[166:167]
	v_pk_add_f32 v[74:75], v[70:71], v[132:133]
	v_lshlrev_b32_e32 v70, 16, v129
	v_pk_mul_f32 v[78:79], v[62:63], v[74:75]
	v_pk_fma_f32 v[62:63], v[62:63], v[74:75], s[2:3]
	v_lshlrev_b32_e32 v75, 16, v188
	v_lshlrev_b32_e32 v62, 16, v125
	v_lshlrev_b32_e32 v132, 16, v127
	v_sub_f32_e32 v70, v70, v62
	v_fmac_f32_e32 v62, v70, v88
	v_sub_f32_e32 v70, v75, v132
	v_fmac_f32_e32 v132, v70, v80
	v_add_f32_e32 v70, v76, v96
	v_max_f32_e64 v75, -v70, 0
	v_mul_f32_e64 v70, |v70|, s65
	v_exp_f32_e32 v70, v70
	v_and_b32_e32 v125, 0xffff0000, v127
	v_sub_f32_e32 v64, v72, v125
	v_fmac_f32_e32 v125, v64, v81
	v_add_f32_e32 v70, 1.0, v70
	v_cmp_gt_f32_e64 s[10:11], s89, v70
	v_add_f32_e32 v64, v77, v97
	v_pk_mul_f32 v[78:79], v[112:113], v[78:79]
	v_cndmask_b32_e64 v76, 0, 32, s[10:11]
	v_ldexp_f32 v70, v70, v76
	v_log_f32_e32 v70, v70
	v_mov_b32_e32 v79, v63
	v_mul_f32_e32 v63, v66, v82
	v_mul_f32_e32 v82, v190, v84
	v_mul_f32_e32 v76, 0x3f317217, v70
	v_fma_f32 v76, v70, s2, -v76
	v_fmac_f32_e32 v76, 0x3377d1cf, v70
	v_fmac_f32_e32 v76, 0x3f317217, v70
	v_cmp_lt_f32_e64 s[12:13], |v70|, s62
	v_mul_f32_e32 v72, v189, v85
	v_mov_b32_e32 v129, v161
	v_cndmask_b32_e64 v70, v70, v76, s[12:13]
	v_cndmask_b32_e64 v76, 0, v229, s[10:11]
	v_sub_f32_e32 v70, v70, v76
	v_max_f32_e64 v76, -v64, 0
	v_mul_f32_e64 v64, |v64|, s65
	v_exp_f32_e32 v64, v64
	v_add_f32_e32 v70, v75, v70
	v_sub_f32_e32 v70, -0.5, v70
	v_mul_f32_e32 v70, 0x3fb8aa3b, v70
	v_add_f32_e32 v64, 1.0, v64
	v_cmp_gt_f32_e64 s[10:11], s89, v64
	v_exp_f32_e32 v70, v70
	v_pk_add_f32 v[94:95], v[82:83], v[130:131]
	v_cndmask_b32_e64 v77, 0, 32, s[10:11]
	v_ldexp_f32 v64, v64, v77
	v_log_f32_e32 v64, v64
	v_mul_f32_e32 v70, 0xbfb8aa3b, v70
	v_exp_f32_e32 v70, v70
	v_pk_mul_f32 v[90:91], v[86:87], v[94:95]
	v_mul_f32_e32 v77, 0x3f317217, v64
	v_fma_f32 v77, v64, s2, -v77
	v_fmac_f32_e32 v77, 0x3377d1cf, v64
	v_fmac_f32_e32 v77, 0x3f317217, v64
	v_cmp_lt_f32_e64 s[12:13], |v64|, s62
	v_sub_f32_e32 v75, 1.0, v70
	v_xor_b32_e32 v141, 0x80000000, v166
	v_cndmask_b32_e64 v64, v64, v77, s[12:13]
	v_cndmask_b32_e64 v77, 0, v229, s[10:11]
	v_sub_f32_e32 v64, v64, v77
	v_add_f32_e32 v64, v76, v64
	v_sub_f32_e32 v64, -0.5, v64
	v_mul_f32_e32 v64, 0x3fb8aa3b, v64
	v_exp_f32_e32 v64, v64
	v_xor_b32_e32 v67, 0x80000000, v78
	v_pk_mul_f32 v[130:131], v[112:113], v[90:91]
	v_pk_fma_f32 v[86:87], v[86:87], v[94:95], s[2:3]
	v_mul_f32_e32 v64, 0xbfb8aa3b, v64
	v_exp_f32_e32 v84, v64
	v_add_f32_e32 v64, v73, v93
	v_mul_f32_e32 v64, 0xbfb8aa3b, v64
	v_exp_f32_e32 v64, v64
	v_sub_f32_e32 v85, 1.0, v84
	v_mul_f32_e32 v70, v62, v70
	v_mov_b32_e32 v131, v87
	v_add_f32_e32 v64, 1.0, v64
	v_rcp_f32_e32 v73, v64
	v_mov_b32_e32 v64, v69
	v_mul_f32_e32 v69, v68, v84
	v_xor_b32_e32 v82, 0x80000000, v130
	v_pk_add_f32 v[76:77], v[72:73], v[128:129]
	v_lshlrev_b32_e32 v87, 16, v118
	v_pk_mul_f32 v[80:81], v[64:65], v[76:77]
	v_pk_fma_f32 v[64:65], v[64:65], v[76:77], s[2:3]
	v_pk_mul_f32 v[80:81], v[112:113], v[80:81]
	v_cvt_pk_bf16_f32 v64, v139, v126
	v_mov_b32_e32 v167, v165
	v_mov_b32_e32 v81, v65
	v_cvt_pk_bf16_f32 v65, v75, v85
	global_store_dwordx2 v[110:111], v[64:65], off offset:1024
	v_cvt_pk_bf16_f32 v64, v140, v63
	v_cvt_pk_bf16_f32 v65, v70, v69
	global_store_dwordx2 v[110:111], v[64:65], off offset:3072
	v_cvt_pk_bf16_f32 v64, v141, v67
	v_xor_b32_e32 v72, 0x80000000, v80
	v_cvt_pk_bf16_f32 v65, v82, v72
	global_store_dwordx2 v[144:145], v[64:65], off offset:1024
	v_lshlrev_b32_e32 v64, 16, v186
	v_sub_f32_e32 v127, v64, v87
	v_and_b32_e32 v89, 0xffff0000, v118
	v_and_b32_e32 v64, 0xffff0000, v186
	v_pk_mul_f32 v[136:137], v[166:167], v[136:137]
	v_sub_f32_e32 v129, v64, v89
	v_lshlrev_b32_e32 v64, 16, v184
	v_lshlrev_b32_e32 v91, 16, v119
	v_mov_b32_e32 v70, v71
	v_mov_b32_e32 v71, v74
	v_lshlrev_b32_e32 v63, 16, v185
	v_lshlrev_b32_e32 v92, 16, v116
	v_sub_f32_e32 v139, v64, v91
	v_and_b32_e32 v93, 0xffff0000, v119
	v_and_b32_e32 v64, 0xffff0000, v184
	v_pk_mul_f32 v[84:85], v[108:109], v[136:137] op_sel_hi:[0,1]
	v_pk_mul_f32 v[70:71], v[78:79], v[70:71]
	v_sub_f32_e32 v126, v63, v92
	v_and_b32_e32 v90, 0xffff0000, v116
	v_and_b32_e32 v63, 0xffff0000, v185
	v_sub_f32_e32 v97, v64, v93
	v_pk_fma_f32 v[64:65], v[0:1], v[134:135], v[162:163] op_sel_hi:[0,1,1]
	v_fmac_f32_e32 v138, v54, v85
	v_pk_mul_f32 v[74:75], v[66:67], v[70:71] op_sel_hi:[0,1]
	v_sub_f32_e32 v128, v63, v90
	v_lshlrev_b32_e32 v63, 16, v123
	v_lshlrev_b32_e32 v88, 16, v117
	v_pk_fma_f32 v[64:65], v[108:109], v[136:137], v[64:65] op_sel_hi:[0,1,1]
	v_fmac_f32_e32 v138, v55, v75
	v_mov_b32_e32 v54, v83
	v_mov_b32_e32 v55, v94
	v_sub_f32_e32 v133, v63, v88
	v_and_b32_e32 v86, 0xffff0000, v117
	v_and_b32_e32 v63, 0xffff0000, v123
	v_pk_fma_f32 v[64:65], v[66:67], v[70:71], v[64:65] op_sel_hi:[0,1,1]
	v_pk_mul_f32 v[54:55], v[130:131], v[54:55]
	v_sub_f32_e32 v96, v63, v86
	v_pk_mul_f32 v[66:67], v[62:63], v[54:55] op_sel_hi:[0,1]
	v_pk_fma_f32 v[62:63], v[62:63], v[54:55], v[64:65] op_sel_hi:[0,1,1]
	v_mov_b32_e32 v64, v73
	v_mov_b32_e32 v65, v76
	v_pk_mul_f32 v[64:65], v[80:81], v[64:65]
	v_fmac_f32_e32 v138, v56, v67
	v_pk_mul_f32 v[66:67], v[68:69], v[64:65] op_sel_hi:[0,1]
	v_fmac_f32_e32 v138, v57, v67
	v_cvt_pk_bf16_f32 v56, v136, v70
	v_cvt_pk_bf16_f32 v57, v54, v64
	global_store_dwordx2 v[144:145], v[56:57], off offset:3072
	v_cvt_pk_bf16_f32 v54, v137, v71
	v_cvt_pk_bf16_f32 v55, v55, v65
	global_store_dwordx2 v[142:143], v[54:55], off offset:1024
	v_cvt_pk_bf16_f32 v54, v114, v124
	v_cvt_pk_bf16_f32 v55, v132, v125
	global_store_dwordx2 v[142:143], v[54:55], off offset:3072
	v_cvt_pk_bf16_f32 v54, v58, v59
	v_cvt_pk_bf16_f32 v55, v60, v61
	global_store_dwordx2 v[106:107], v[54:55], off
	v_pk_fma_f32 v[94:95], v[68:69], v[64:65], v[62:63] op_sel_hi:[0,1,1]
	ds_read_b128 v[70:73], v179 offset:8384
	ds_read_b128 v[66:69], v179 offset:10432
	ds_read_b128 v[62:65], v179 offset:12480
	ds_read_b128 v[58:61], v179 offset:14528
	ds_read_b128 v[54:57], v179 offset:16576
	ds_read_b128 v[74:77], v179 offset:18624
	ds_read_b128 v[78:81], v179 offset:22720
	ds_read_b128 v[82:85], v179 offset:20672
	ds_read_b128 v[116:119], v174 offset:35840
	s_waitcnt lgkmcnt(0)
	v_mfma_f32_16x16x32_bf16 v[50:53], v[116:119], v[50:53], 0
	ds_read_b128 v[116:119], v174 offset:39936
	v_mov_b32_e32 v123, v161
	v_fmac_f32_e32 v92, v126, v74
	s_waitcnt lgkmcnt(0)
	v_mfma_f32_16x16x32_bf16 v[46:49], v[116:119], v[46:49], v[50:53]
	s_nop 2
	ds_read_b128 v[50:53], v174 offset:44032
	v_fmac_f32_e32 v90, v128, v75
	v_mov_b32_e32 v160, v115
	s_waitcnt lgkmcnt(0)
	v_mfma_f32_16x16x32_bf16 v[42:45], v[50:53], v[42:45], v[46:49]
	v_mov_b32_e32 v50, v62
	v_mov_b32_e32 v51, v58
	v_mov_b32_e32 v58, v63
	v_mfma_f32_16x16x32_bf16 v[46:49], v[26:29], v[34:37], 0
	v_fmac_f32_e32 v89, v129, v79
	v_fmac_f32_e32 v88, v133, v76
	v_fmac_f32_e32 v87, v127, v78
	v_mfma_f32_16x16x32_bf16 v[34:37], v[30:33], v[38:41], 0
	v_mul_f32_e32 v38, v187, v82
	s_nop 2
	v_add_f32_e32 v0, v70, v46
	v_max_f32_e64 v39, -v0, 0
	v_mul_f32_e64 v0, |v0|, s65
	v_exp_f32_e32 v0, v0
	v_add_f32_e32 v34, v66, v34
	v_mul_f32_e32 v34, 0xbfb8aa3b, v34
	v_exp_f32_e32 v34, v34
	v_add_f32_e32 v0, 1.0, v0
	v_cmp_gt_f32_e64 s[10:11], s89, v0
	v_add_f32_e32 v35, v67, v35
	v_add_f32_e32 v34, 1.0, v34
	v_cndmask_b32_e64 v40, 0, 32, s[10:11]
	v_ldexp_f32 v0, v0, v40
	v_log_f32_e32 v0, v0
	v_mul_f32_e32 v35, 0xbfb8aa3b, v35
	v_exp_f32_e32 v35, v35
	v_add_f32_e32 v36, v68, v36
	v_mul_f32_e32 v40, 0x3f317217, v0
	v_fma_f32 v40, v0, s2, -v40
	v_fmac_f32_e32 v40, 0x3377d1cf, v0
	v_fmac_f32_e32 v40, 0x3f317217, v0
	v_cmp_lt_f32_e64 s[12:13], |v0|, s62
	v_add_f32_e32 v35, 1.0, v35
	v_rcp_f32_e32 v35, v35
	v_cndmask_b32_e64 v0, v0, v40, s[12:13]
	v_cndmask_b32_e64 v40, 0, v229, s[10:11]
	v_sub_f32_e32 v0, v0, v40
	v_add_f32_e32 v0, v39, v0
	v_rcp_f32_e32 v39, v34
	v_mul_f32_e32 v34, v121, v83
	v_mov_b32_e32 v121, v161
	v_mul_f32_e32 v36, 0xbfb8aa3b, v36
	v_pk_add_f32 v[40:41], v[38:39], v[122:123]
	v_mov_b32_e32 v38, v39
	v_pk_mul_f32 v[52:53], v[50:51], v[40:41]
	v_pk_fma_f32 v[50:51], v[50:51], v[40:41], s[2:3]
	v_pk_mul_f32 v[52:53], v[112:113], v[52:53]
	v_mov_b32_e32 v39, v40
	v_mov_b32_e32 v53, v51
	v_pk_mul_f32 v[38:39], v[52:53], v[38:39]
	v_xor_b32_e32 v62, 0x80000000, v52
	v_pk_mul_f32 v[40:41], v[92:93], v[38:39] op_sel_hi:[0,1]
	v_add_f32_e32 v40, v71, v47
	v_fmac_f32_e32 v138, v54, v41
	v_max_f32_e64 v41, -v40, 0
	v_mul_f32_e64 v40, |v40|, s65
	v_exp_f32_e32 v40, v40
	v_exp_f32_e32 v36, v36
	v_add_f32_e32 v37, v69, v37
	v_mul_f32_e32 v37, 0xbfb8aa3b, v37
	v_add_f32_e32 v40, 1.0, v40
	v_cmp_gt_f32_e64 s[10:11], s89, v40
	v_add_f32_e32 v36, 1.0, v36
	v_exp_f32_e32 v37, v37
	v_cndmask_b32_e64 v46, 0, 32, s[10:11]
	v_ldexp_f32 v40, v40, v46
	v_log_f32_e32 v40, v40
	v_sub_f32_e32 v0, -0.5, v0
	v_add_f32_e32 v37, 1.0, v37
	v_mul_f32_e32 v0, 0x3fb8aa3b, v0
	v_mul_f32_e32 v46, 0x3f317217, v40
	v_fma_f32 v46, v40, s2, -v46
	v_fmac_f32_e32 v46, 0x3377d1cf, v40
	v_fmac_f32_e32 v46, 0x3f317217, v40
	v_cmp_lt_f32_e64 s[12:13], |v40|, s62
	v_rcp_f32_e32 v37, v37
	v_exp_f32_e32 v0, v0
	v_cndmask_b32_e64 v40, v40, v46, s[12:13]
	v_cndmask_b32_e64 v46, 0, v229, s[10:11]
	v_sub_f32_e32 v40, v40, v46
	v_add_f32_e32 v40, v41, v40
	v_sub_f32_e32 v40, -0.5, v40
	v_mul_f32_e32 v40, 0x3fb8aa3b, v40
	v_exp_f32_e32 v40, v40
	v_mul_f32_e32 v0, 0xbfb8aa3b, v0
	v_exp_f32_e32 v0, v0
	v_fmac_f32_e32 v86, v96, v77
	v_mul_f32_e32 v40, 0xbfb8aa3b, v40
	v_exp_f32_e32 v54, v40
	v_pk_add_f32 v[40:41], v[34:35], v[120:121]
	v_mov_b32_e32 v34, v35
	v_pk_mul_f32 v[46:47], v[58:59], v[40:41]
	v_pk_fma_f32 v[52:53], v[58:59], v[40:41], s[2:3]
	v_pk_mul_f32 v[46:47], v[112:113], v[46:47]
	v_mov_b32_e32 v35, v40
	v_mov_b32_e32 v47, v53
	v_pk_mul_f32 v[34:35], v[46:47], v[34:35]
	v_xor_b32_e32 v59, 0x80000000, v46
	v_pk_mul_f32 v[40:41], v[90:91], v[34:35] op_sel_hi:[0,1]
	v_fmac_f32_e32 v138, v55, v41
	v_add_f32_e32 v41, v72, v48
	v_max_f32_e64 v46, -v41, 0
	v_mul_f32_e64 v41, |v41|, s65
	v_exp_f32_e32 v41, v41
	v_mul_f32_e32 v40, v183, v84
	v_mov_b32_e32 v52, v64
	v_mov_b32_e32 v53, v60
	v_add_f32_e32 v41, 1.0, v41
	v_cmp_gt_f32_e64 s[10:11], s89, v41
	v_sub_f32_e32 v66, 1.0, v54
	v_mul_f32_e32 v58, v90, v54
	v_cndmask_b32_e64 v47, 0, 32, s[10:11]
	v_ldexp_f32 v41, v41, v47
	v_log_f32_e32 v41, v41
	v_mov_b32_e32 v60, v65
	v_sub_f32_e32 v70, 1.0, v0
	v_mul_f32_e32 v0, v92, v0
	v_mul_f32_e32 v47, 0x3f317217, v41
	v_fma_f32 v47, v41, s2, -v47
	v_fmac_f32_e32 v47, 0x3377d1cf, v41
	v_fmac_f32_e32 v47, 0x3f317217, v41
	v_cmp_lt_f32_e64 s[12:13], |v41|, s62
	v_pk_fma_f32 v[50:51], v[92:93], v[38:39], v[94:95] op_sel_hi:[0,1,1]
	v_pk_fma_f32 v[50:51], v[90:91], v[34:35], v[50:51] op_sel_hi:[0,1,1]
	v_cndmask_b32_e64 v41, v41, v47, s[12:13]
	v_cndmask_b32_e64 v47, 0, v229, s[10:11]
	v_sub_f32_e32 v41, v41, v47
	v_add_f32_e32 v41, v46, v41
	v_sub_f32_e32 v41, -0.5, v41
	v_mul_f32_e32 v41, 0x3fb8aa3b, v41
	v_exp_f32_e32 v41, v41
	v_fmac_f32_e32 v91, v139, v80
	v_fmac_f32_e32 v93, v97, v81
	v_mul_f32_e32 v41, 0xbfb8aa3b, v41
	v_exp_f32_e32 v48, v41
	v_rcp_f32_e32 v41, v36
	v_mul_f32_e32 v36, v182, v85
	v_sub_f32_e32 v63, 1.0, v48
	v_pk_add_f32 v[46:47], v[40:41], v[160:161]
	v_mov_b32_e32 v40, v41
	v_pk_mul_f32 v[54:55], v[52:53], v[46:47]
	v_pk_fma_f32 v[52:53], v[52:53], v[46:47], s[2:3]
	v_pk_mul_f32 v[54:55], v[112:113], v[54:55]
	v_mov_b32_e32 v41, v46
	v_mov_b32_e32 v55, v53
	v_pk_mul_f32 v[40:41], v[54:55], v[40:41]
	v_mul_f32_e32 v55, v88, v48
	v_pk_mul_f32 v[46:47], v[88:89], v[40:41] op_sel_hi:[0,1]
	v_add_f32_e32 v46, v73, v49
	v_fmac_f32_e32 v138, v56, v47
	v_max_f32_e64 v47, -v46, 0
	v_mul_f32_e64 v46, |v46|, s65
	v_exp_f32_e32 v46, v46
	v_mov_b32_e32 v160, v109
	v_xor_b32_e32 v54, 0x80000000, v54
	v_pk_fma_f32 v[50:51], v[88:89], v[40:41], v[50:51] op_sel_hi:[0,1,1]
	v_add_f32_e32 v46, 1.0, v46
	v_cmp_gt_f32_e64 s[10:11], s89, v46
	s_nop 1
	v_cndmask_b32_e64 v48, 0, 32, s[10:11]
	v_ldexp_f32 v46, v46, v48
	v_log_f32_e32 v46, v46
	s_nop 0
	v_mul_f32_e32 v48, 0x3f317217, v46
	v_fma_f32 v48, v46, s2, -v48
	v_fmac_f32_e32 v48, 0x3377d1cf, v46
	v_fmac_f32_e32 v48, 0x3f317217, v46
	v_cmp_lt_f32_e64 s[12:13], |v46|, s62
	s_nop 1
	v_cndmask_b32_e64 v46, v46, v48, s[12:13]
	v_cndmask_b32_e64 v48, 0, v229, s[10:11]
	v_sub_f32_e32 v46, v46, v48
	v_add_f32_e32 v46, v47, v46
	v_sub_f32_e32 v46, -0.5, v46
	v_mul_f32_e32 v46, 0x3fb8aa3b, v46
	v_exp_f32_e32 v46, v46
	s_nop 0
	v_mul_f32_e32 v46, 0xbfb8aa3b, v46
	v_exp_f32_e32 v56, v46
	v_pk_add_f32 v[46:47], v[36:37], v[160:161]
	v_sub_f32_e32 v64, 1.0, v56
	v_pk_mul_f32 v[48:49], v[60:61], v[46:47]
	v_pk_fma_f32 v[52:53], v[60:61], v[46:47], s[2:3]
	v_pk_mul_f32 v[48:49], v[112:113], v[48:49]
	v_pk_mov_b32 v[36:37], v[36:37], v[46:47] op_sel:[1,0]
	v_mov_b32_e32 v49, v53
	v_pk_mul_f32 v[36:37], v[48:49], v[36:37]
	v_mul_f32_e32 v49, v86, v56
	v_pk_mul_f32 v[46:47], v[86:87], v[36:37] op_sel_hi:[0,1]
	v_fmac_f32_e32 v138, v57, v47
	v_cvt_pk_bf16_f32 v46, v70, v66
	v_cvt_pk_bf16_f32 v47, v63, v64
	global_store_dwordx2 v[110:111], v[46:47], off offset:1536
	v_cvt_pk_bf16_f32 v46, v0, v58
	v_cvt_pk_bf16_f32 v47, v55, v49
	v_xor_b32_e32 v48, 0x80000000, v48
	global_store_dwordx2 v[110:111], v[46:47], off offset:3584
	v_cvt_pk_bf16_f32 v46, v62, v59
	v_cvt_pk_bf16_f32 v47, v54, v48
	global_store_dwordx2 v[144:145], v[46:47], off offset:1536
	v_cvt_pk_bf16_f32 v46, v38, v34
	v_cvt_pk_bf16_f32 v47, v40, v36
	global_store_dwordx2 v[144:145], v[46:47], off offset:3584
	v_cvt_pk_bf16_f32 v34, v39, v35
	v_cvt_pk_bf16_f32 v35, v41, v37
	global_store_dwordx2 v[142:143], v[34:35], off offset:1536
	v_cvt_pk_bf16_f32 v34, v87, v89
	v_cvt_pk_bf16_f32 v35, v91, v93
	v_pk_fma_f32 v[50:51], v[86:87], v[36:37], v[50:51] op_sel_hi:[0,1,1]
	global_store_dwordx2 v[142:143], v[34:35], off offset:3584
	v_cvt_pk_bf16_f32 v34, v42, v43
	v_cvt_pk_bf16_f32 v35, v44, v45
	global_store_dwordx2 v[106:107], v[34:35], off offset:512
	ds_bpermute_b32 v34, v177, v50
	ds_bpermute_b32 v35, v177, v51
	ds_bpermute_b32 v0, v177, v138
	s_waitcnt lgkmcnt(1)
	v_pk_add_f32 v[34:35], v[50:51], v[34:35]
	s_waitcnt lgkmcnt(0)
	v_add_f32_e32 v0, v138, v0
	ds_bpermute_b32 v36, v178, v34
	ds_bpermute_b32 v37, v178, v35
	ds_bpermute_b32 v38, v178, v0
	s_and_saveexec_b64 s[10:11], s[8:9]
	s_cbranch_execz .LBB0_845
	s_lshl_b64 s[12:13], s[22:23], 16
	s_add_u32 s12, s58, s12
	s_addc_u32 s13, s59, s13
	v_lshlrev_b32_e32 v39, 4, v181
	s_waitcnt lgkmcnt(1)
	v_pk_add_f32 v[34:35], v[34:35], v[36:37]
	s_waitcnt lgkmcnt(0)
	v_add_f32_e32 v36, v0, v38
	v_mov_b32_e32 v37, v1
	global_store_dwordx4 v39, v[34:37], s[12:13]
	s_branch .LBB0_845
